# MoBA units dealt to workgroups by own = j xor {31,4,10,17}[round] so no workgroup gets two of the cheap early-block units (load balance)
# baseline (speedup 1.0000x reference)
; __device__ __forceinline__ int opaque_tid() { int t = threadIdx.x; asm volatile("" : "+v"(t)); return t; }
; #define LAS __attribute__((address_space(3)))
; #define INP(k) ((const float*)(const GASP float*)ldptr(PT, (k)))
; #define WSP(T, off) ((T*)(GASP T*)(ldptr(PT, 26) + (off)))
; __device__ __forceinline__ void moba_unit2(lbyte* lds, const bf16* QKV, bf16* AO, unsigned char* part, unsigned char* part3, const float* km2, const float* rel_bias, int b, int hm, int own) {
;     const int tid = pg8::opaque_tid(), wid = __builtin_amdgcn_readfirstlane(tid >> 6), lane = tid & 63, l31 = lane & 31, h = lane >> 5;
;     const int ocol = (8 + hm) * 64; const size_t rowbase = (size_t)b * SEQ, hbase = ((size_t)(b * 8 + hm) * SEQ) * 64;
;     const bf16* Qh = QKV + 3 * EVSEG + hbase; const bf16* Kh = QKV + 4 * EVSEG + hbase; const bf16* Vh = QKV + 5 * EVSEG + hbase;
;     LAS float* kmean = (LAS float*)(lds + MC_KMEAN); LAS unsigned short* list = (LAS unsigned short*)(lds + MC_LIST); LAS unsigned* cnt = (LAS unsigned*)(lds + MC_CNT);
;     LAS unsigned* istart = cnt + 32; LAS unsigned* ctr = cnt + 72; LAS float* dtab = (LAS float*)(lds + MC_DTAB); LAS float* tab = (LAS float*)(lds + MC_TAB); LAS int* thr = (LAS int*)(lds + MC_TAB + 128);
;     lbyte* kbuf = lds + MC_WB + wid * MC_WBSZ; lbyte* vbuf = kbuf + 32 * KP64;
;     for (int i = tid; i < 256 * 8; i += NT) { const int row = i >> 3, ch = i & 7; *(LAS u32x4*)(lds + MC_Q + row * KP64 + ch * 16) = *(const u32x4*)(Qh + ((size_t)own * 256 + row) * 64 + ch * 8); }
; __global__ void __launch_bounds__(NT, 2) trunk_fwd(Args args) {
;     ...
;                     const int rnd = u / 256, w = u % 256, x = w % 8, j = w / 8, pr = 4 * x + (rnd & 3), b = pr / 8, hh = pr % 8;
;                     if (rnd < 4) {
;     ...
;                         moba_unit(lds, WSP(bf16, WS_QKV), WSP(bf16, WS_AO), WSP(float, WS_KM2), INP(2), b, hh, (rnd & 1) ? j : 31 - j);
;     ...
;                         moba_unit2(lds, WSP(bf16, WS_QKV), WSP(bf16, WS_AO), WSP(unsigned char, WS_CQ) + (size_t)bx * PART_SLAB, WSP(unsigned char, WS_HALO) + (size_t)bx * (256 * PART_PITCH), WSP(float, WS_KM2), INP(2), b, hh, (rnd & 1) ? j : 31 - j);
.LBB0_561:
	s_and_b64 vcc, exec, s[0:1]
	s_cbranch_vccz .LBB0_552
	s_waitcnt lgkmcnt(0)
	v_readfirstlane_b32 s53, v114
	v_mov_b32_e32 v0, s37
	v_readfirstlane_b32 s51, v115
	s_add_u32 s11, s53, 0xac00000
	ds_read_b64 v[2:3], v0
	s_addc_u32 s14, s51, 0
	s_lshl_b32 s4, s8, 3
	s_lshr_b32 s4, 0x110a041f, s4
	s_and_b32 s4, s4, 31
	s_xor_b32 s38, s9, s4
	s_lshl_b32 s4, s12, 3
	s_add_i32 s4, s4, s16
	s_waitcnt lgkmcnt(0)
	v_readfirstlane_b32 s0, v2
	v_mov_b32_e32 v2, v232
	s_ashr_i32 s5, s4, 31
	s_movk_i32 s8, 0x800
	v_readfirstlane_b32 s1, v3
	s_lshl_b64 s[6:7], s[4:5], 19
	v_readfirstlane_b32 s10, v2
	v_cmp_gt_i32_e32 vcc, s8, v2
	v_lshlrev_b32_e32 v4, 4, v2
	s_and_saveexec_b64 s[8:9], vcc
	s_cbranch_execz .LBB0_565
	s_lshl_b64 s[20:21], s[6:7], 1
	s_add_u32 s13, s11, s20
	s_addc_u32 s15, s14, s21
	s_ashr_i32 s39, s38, 31
	s_lshl_b64 s[20:21], s[38:39], 15
	s_add_u32 s20, s13, s20
	s_addc_u32 s21, s15, s21
	v_and_b32_e32 v0, 0x70, v4
	v_lshl_add_u64 v[6:7], s[20:21], 0, v[0:1]
	s_mov_b64 s[20:21], 0x6000000
	v_lshl_add_u64 v[6:7], v[6:7], 0, s[20:21]
	v_add_u32_e32 v0, 0, v0
	s_mov_b64 s[20:21], 0
	v_mov_b32_e32 v3, v2
